# one static s_setprio 1 for waves 4-7 at entry of swiglu/proj GEMM loops and both attention loops, reset at exit
# baseline (speedup 1.0000x reference)
; #define MFMA32(a, b, c) __builtin_amdgcn_mfma_f32_32x32x16_bf16((a), (b), (c), 0, 0, 0)
; template <int DK>
; DI void attn_item(const Params& p, int layer, int b, int hd, int qt, int ctxq, char* smem) {
;     ...
;     for (int kt = 0; kt < nkt; ++kt) {
;         const int cur = kt & 1;
;         const bf16_t* kb_ = sK + cur * 64 * 72; const bf16_t* vb_ = sV + cur * 64 * 68;
; #pragma unroll
;         for (int s = 0; s < 2; ++s) {
;             if (s == 1) {
;                 if (kt + 1 < nkt) {
; #pragma unroll
;                     for (int i = 0; i < 2; ++i) { rk[i] = *(const u32x4*)(Kg + (size_t)((kt + 1) * 64 + srow + 32 * i) * 64 + sc8); rv[i] = *(const u32x4*)(Vg + (size_t)(srow + 32 * i) * NKEY + (kt + 1) * 64 + sc8); }
;                 }
;             }
;             f32x16 x[2];
; #pragma unroll
;             for (int kb = 0; kb < 2; ++kb)
; #pragma unroll
;                 for (int i = 0; i < 16; ++i) x[kb][i] = 0.f;
;             const int kofs = DK == 32 ? 32 * s : 0;
; #pragma unroll
;             for (int ks = 0; ks < NKS; ++ks) {
;                 const bf16x8 a0 = *(const bf16x8*)(kb_ + r * 72 + kofs + 16 * ks + 8 * h), a1 = *(const bf16x8*)(kb_ + (32 + r) * 72 + kofs + 16 * ks + 8 * h);
;                 const bf16x8 qv = *(const bf16x8*)(sQ + ((s * NKS + ks) * 64 + lane) * 8);
;                 x[0] = MFMA32(a0, qv, x[0]); x[1] = MFMA32(a1, qv, x[1]);
;             }
.LBB0_145:
	s_mov_b32 s21, 0
	v_readfirstlane_b32 s9, v163
	s_bitcmp1_b32 s9, 8
	s_cbranch_scc0 .Lprio_a64
	s_setprio 1
.Lprio_a64:
	ds_read_b128 v[212:215], v182 offset:35840
	ds_read_b128 v[216:219], v182 offset:36864
	ds_read_b128 v[220:223], v182 offset:37888
	ds_read_b128 v[184:187], v182 offset:38912
	ds_read_b128 v[128:131], v181
	ds_read_b128 v[132:135], v181 offset:32
	ds_read_b128 v[136:139], v181 offset:64
	ds_read_b128 v[140:143], v181 offset:96
	ds_read_b128 v[144:147], v181 offset:4608
	ds_read_b128 v[148:151], v181 offset:4640
	ds_read_b128 v[152:155], v181 offset:4672
	ds_read_b128 v[192:195], v181 offset:4704
	v_lshl_add_u64 v[176:177], v[176:177], 0, v[160:161]
	v_lshl_add_u64 v[178:179], v[178:179], 0, v[160:161]
	s_mov_b64 s[8:9], 0x3000
	v_lshl_add_u64 v[178:179], v[178:179], 0, s[8:9]
	global_load_dwordx4 v[196:199], v[178:179], off offset:-4096
	global_load_dwordx4 v[200:203], v[178:179], off
	global_load_dwordx4 v[204:207], v[176:177], off offset:128
	s_mov_b64 s[8:9], 0x84000
	v_lshl_add_u64 v[176:177], v[176:177], 0, s[8:9]
	global_load_dwordx4 v[208:211], v[176:177], off offset:128
	v_mov_b32_e32 v157, v156
	v_mov_b32_e32 v173, v172

; #define MFMA32(a, b, c) __builtin_amdgcn_mfma_f32_32x32x16_bf16((a), (b), (c), 0, 0, 0)
; template <int DK>
; DI void attn_item(const Params& p, int layer, int b, int hd, int qt, int ctxq, char* smem) {
;     ...
;             const f32x2 mref = {m_[s], m_[s]};
;             float ps = 0.f;
; #pragma unroll
;             for (int kb = 0; kb < 2; ++kb)
; #pragma unroll
;                 for (int i2 = 0; i2 < 8; ++i2) {
;                     f32x2 t = {x[kb][2 * i2], x[kb][2 * i2 + 1]};
;                     asm("v_pk_add_f32 %0, %1, %2 neg_lo:[0,1] neg_hi:[0,1]" : "=v"(t) : "v"(t), "v"(mref));
;                     const float e0 = __builtin_amdgcn_exp2f(t.x), e1 = __builtin_amdgcn_exp2f(t.y);
;                     x[kb][2 * i2] = e0; x[kb][2 * i2 + 1] = e1; ps += e0 + e1;
;                 }
;             l_[s] += ps;
; #pragma unroll
;             for (int kb = 0; kb < 2; ++kb)
; #pragma unroll
;                 for (int st = 0; st < 2; ++st) {
;                     u32x4 w;
;                     w.x = pk_bf16(x[kb][8 * st], x[kb][8 * st + 1]); w.y = pk_bf16(x[kb][8 * st + 2], x[kb][8 * st + 3]);
;                     w.z = pk_bf16(x[kb][8 * st + 4], x[kb][8 * st + 5]); w.w = pk_bf16(x[kb][8 * st + 6], x[kb][8 * st + 7]);
;                     const bf16x8 pfr = __builtin_bit_cast(bf16x8, w);
; #pragma unroll
;                     for (int d = 0; d < 2; ++d) {
;                         const bf16_t* vp = vb_ + (32 * d + r) * 68 + 32 * kb + 16 * st + 4 * h;
;                         const s16x4 lo = *(const s16x4*)vp, hi = *(const s16x4*)(vp + 8);
;                         const bf16x8 vf = __builtin_shufflevector(lo, hi, 0, 1, 2, 3, 4, 5, 6, 7);
;                         O[s][d] = MFMA32(vf, pfr, O[s][d]);
;                     }
;                 }
;         }
;         if (kt + 1 < nkt) {
;             bf16_t* wk = sK + (cur ^ 1) * 64 * 72; bf16_t* wv = sV + (cur ^ 1) * 64 * 68;
; #pragma unroll
;             for (int i = 0; i < 2; ++i) {
;                 *(u32x4*)(wk + (srow + 32 * i) * 72 + sc8) = rk[i];
;                 *(u32x2*)(wv + (srow + 32 * i) * 68 + sc8) = (u32x2){rv[i].x, rv[i].y}; *(u32x2*)(wv + (srow + 32 * i) * 68 + sc8 + 4) = (u32x2){rv[i].z, rv[i].w};
;             }
;         }
;         __syncthreads();
.Lat64_nors1:
	v_pk_add_f32 v[80:81], v[80:81], v[172:173] neg_lo:[0,1] neg_hi:[0,1]
	v_pk_add_f32 v[82:83], v[82:83], v[172:173] neg_lo:[0,1] neg_hi:[0,1]
	v_pk_add_f32 v[84:85], v[84:85], v[172:173] neg_lo:[0,1] neg_hi:[0,1]
	v_pk_add_f32 v[86:87], v[86:87], v[172:173] neg_lo:[0,1] neg_hi:[0,1]
	v_exp_f32_e32 v80, v80
	v_exp_f32_e32 v81, v81
	v_exp_f32_e32 v82, v82
	v_exp_f32_e32 v83, v83
	v_exp_f32_e32 v84, v84
	v_exp_f32_e32 v85, v85
	v_exp_f32_e32 v86, v86
	v_exp_f32_e32 v87, v87
	v_add_f32_e32 v233, v80, v82
	v_add_f32_e32 v234, v81, v83
	v_add_f32_e32 v233, v233, v84
	v_add_f32_e32 v234, v234, v85
	v_add_f32_e32 v233, v233, v86
	v_add_f32_e32 v234, v234, v87
	v_cvt_pk_bf16_f32 v80, v80, v81
	v_cvt_pk_bf16_f32 v81, v82, v83
	v_cvt_pk_bf16_f32 v82, v84, v85
	v_cvt_pk_bf16_f32 v83, v86, v87
	v_pk_add_f32 v[88:89], v[88:89], v[172:173] neg_lo:[0,1] neg_hi:[0,1]
	v_pk_add_f32 v[90:91], v[90:91], v[172:173] neg_lo:[0,1] neg_hi:[0,1]
	v_pk_add_f32 v[92:93], v[92:93], v[172:173] neg_lo:[0,1] neg_hi:[0,1]
	v_pk_add_f32 v[94:95], v[94:95], v[172:173] neg_lo:[0,1] neg_hi:[0,1]
	v_mfma_f32_32x32x16_bf16 v[16:31], v[96:99], v[80:83], v[16:31]
	v_mfma_f32_32x32x16_bf16 v[0:15], v[112:115], v[80:83], v[0:15]
	v_exp_f32_e32 v88, v88
	v_exp_f32_e32 v89, v89
	v_exp_f32_e32 v90, v90
	v_exp_f32_e32 v91, v91
	v_exp_f32_e32 v92, v92
	v_exp_f32_e32 v93, v93
	v_exp_f32_e32 v94, v94
	v_exp_f32_e32 v95, v95
	v_add_f32_e32 v233, v233, v88
	v_add_f32_e32 v234, v234, v89
	v_add_f32_e32 v233, v233, v90
	v_add_f32_e32 v234, v234, v91
	v_add_f32_e32 v233, v233, v92
	v_add_f32_e32 v234, v234, v93
	v_add_f32_e32 v233, v233, v94
	v_add_f32_e32 v234, v234, v95
	v_cvt_pk_bf16_f32 v88, v88, v89
	v_cvt_pk_bf16_f32 v89, v90, v91
	v_cvt_pk_bf16_f32 v90, v92, v93
	v_cvt_pk_bf16_f32 v91, v94, v95
	v_pk_add_f32 v[64:65], v[64:65], v[172:173] neg_lo:[0,1] neg_hi:[0,1]
	v_pk_add_f32 v[66:67], v[66:67], v[172:173] neg_lo:[0,1] neg_hi:[0,1]
	v_pk_add_f32 v[68:69], v[68:69], v[172:173] neg_lo:[0,1] neg_hi:[0,1]
	v_pk_add_f32 v[70:71], v[70:71], v[172:173] neg_lo:[0,1] neg_hi:[0,1]
	v_mfma_f32_32x32x16_bf16 v[16:31], v[100:103], v[88:91], v[16:31]
	v_mfma_f32_32x32x16_bf16 v[0:15], v[116:119], v[88:91], v[0:15]
	s_waitcnt lgkmcnt(0)
	s_barrier
	ds_read_b128 v[128:131], v175
	ds_read_b128 v[132:135], v175 offset:32
	ds_read_b128 v[136:139], v175 offset:64
	ds_read_b128 v[140:143], v175 offset:96
	ds_read_b128 v[144:147], v175 offset:4608
	ds_read_b128 v[148:151], v175 offset:4640
	ds_read_b128 v[152:155], v175 offset:4672
	ds_read_b128 v[192:195], v175 offset:4704
	ds_read_b128 v[212:215], v182 offset:35840
	ds_read_b128 v[216:219], v182 offset:36864
	ds_read_b128 v[220:223], v182 offset:37888
	ds_read_b128 v[184:187], v182 offset:38912
	v_exp_f32_e32 v64, v64
	v_exp_f32_e32 v65, v65
	v_exp_f32_e32 v66, v66
	v_exp_f32_e32 v67, v67
	v_exp_f32_e32 v68, v68
	v_exp_f32_e32 v69, v69
	v_exp_f32_e32 v70, v70
	v_exp_f32_e32 v71, v71
	v_add_f32_e32 v233, v233, v64
	v_add_f32_e32 v234, v234, v65
	v_add_f32_e32 v233, v233, v66
	v_add_f32_e32 v234, v234, v67
	v_add_f32_e32 v233, v233, v68
	v_add_f32_e32 v234, v234, v69
	v_add_f32_e32 v233, v233, v70
	v_add_f32_e32 v234, v234, v71
	v_cvt_pk_bf16_f32 v64, v64, v65
	v_cvt_pk_bf16_f32 v65, v66, v67
	v_cvt_pk_bf16_f32 v66, v68, v69
	v_cvt_pk_bf16_f32 v67, v70, v71
	v_pk_add_f32 v[72:73], v[72:73], v[172:173] neg_lo:[0,1] neg_hi:[0,1]
	v_pk_add_f32 v[74:75], v[74:75], v[172:173] neg_lo:[0,1] neg_hi:[0,1]
	v_pk_add_f32 v[76:77], v[76:77], v[172:173] neg_lo:[0,1] neg_hi:[0,1]
	v_pk_add_f32 v[78:79], v[78:79], v[172:173] neg_lo:[0,1] neg_hi:[0,1]
	v_mfma_f32_32x32x16_bf16 v[16:31], v[104:107], v[64:67], v[16:31]
	v_mfma_f32_32x32x16_bf16 v[0:15], v[120:123], v[64:67], v[0:15]
	v_exp_f32_e32 v72, v72
	v_exp_f32_e32 v73, v73
	v_exp_f32_e32 v74, v74
	v_exp_f32_e32 v75, v75
	v_exp_f32_e32 v76, v76
	v_exp_f32_e32 v77, v77
	v_exp_f32_e32 v78, v78
	v_exp_f32_e32 v79, v79
	v_add_f32_e32 v233, v233, v72
	v_add_f32_e32 v234, v234, v73
	v_add_f32_e32 v233, v233, v74
	v_add_f32_e32 v234, v234, v75
	v_add_f32_e32 v233, v233, v76
	v_add_f32_e32 v234, v234, v77
	v_add_f32_e32 v233, v233, v78
	v_add_f32_e32 v234, v234, v79
	v_cvt_pk_bf16_f32 v72, v72, v73
	v_cvt_pk_bf16_f32 v73, v74, v75
	v_cvt_pk_bf16_f32 v74, v76, v77
	v_cvt_pk_bf16_f32 v75, v78, v79
	v_add_f32_e32 v233, v233, v234
	v_add_f32_e32 v180, v180, v233
	v_mfma_f32_32x32x16_bf16 v[16:31], v[108:111], v[72:75], v[16:31]
	v_mfma_f32_32x32x16_bf16 v[0:15], v[124:127], v[72:75], v[0:15]
	s_add_i32 s21, s21, 1
	s_cmpk_eq_i32 s21, 0x83
	s_cbranch_scc0 .Lat64_loop
	s_waitcnt lgkmcnt(0)
	s_setprio 0

; #define MFMA32(a, b, c) __builtin_amdgcn_mfma_f32_32x32x16_bf16((a), (b), (c), 0, 0, 0)
; DI float shx(float v, int lane, int m) { return __int_as_float(__builtin_amdgcn_ds_bpermute((lane ^ m) << 2, __float_as_int(v))); }
; template <int DK>
; DI void attn_item(const Params& p, int layer, int b, int hd, int qt, int ctxq, char* smem) {
;     ...
;     for (int kt = 0; kt < nkt; ++kt) {
;         const int cur = kt & 1;
;         const bf16_t* kb_ = sK + cur * 64 * 72; const bf16_t* vb_ = sV + cur * 64 * 68;
; #pragma unroll
;         for (int s = 0; s < 2; ++s) {
;             if (s == 1) {
;                 if (kt + 1 < nkt) {
; #pragma unroll
;                     for (int i = 0; i < 2; ++i) { rk[i] = *(const u32x4*)(Kg + (size_t)((kt + 1) * 64 + srow + 32 * i) * 64 + sc8); rv[i] = *(const u32x4*)(Vg + (size_t)(srow + 32 * i) * NKEY + (kt + 1) * 64 + sc8); }
;                 }
;             }
;             f32x16 x[2];
; #pragma unroll
;             for (int kb = 0; kb < 2; ++kb)
; #pragma unroll
;                 for (int i = 0; i < 16; ++i) x[kb][i] = 0.f;
;             const int kofs = DK == 32 ? 32 * s : 0;
; #pragma unroll
;             for (int ks = 0; ks < NKS; ++ks) {
;                 const bf16x8 a0 = *(const bf16x8*)(kb_ + r * 72 + kofs + 16 * ks + 8 * h), a1 = *(const bf16x8*)(kb_ + (32 + r) * 72 + kofs + 16 * ks + 8 * h);
;                 const bf16x8 qv = *(const bf16x8*)(sQ + ((s * NKS + ks) * 64 + lane) * 8);
;                 x[0] = MFMA32(a0, qv, x[0]); x[1] = MFMA32(a1, qv, x[1]);
;             }
;             float mx = x[0][0];
; #pragma unroll
;             for (int i = 1; i < 16; ++i) mx = fmaxf(mx, x[0][i]);
; #pragma unroll
;             for (int i = 0; i < 16; ++i) mx = fmaxf(mx, x[1][i]);
;             mx = fmaxf(mx, shx(mx, lane, 32));
;             if (__builtin_amdgcn_ballot_w64(mx > m_[s] + 8.f) != 0) {
;                 const float mn = fmaxf(m_[s], mx);
;                 const float al = __builtin_amdgcn_exp2f(m_[s] - mn);
;                 m_[s] = mn;
;                 l_[s] *= al;
; #pragma unroll
;                 for (int d = 0; d < 2; ++d)
; #pragma unroll
;                     for (int i = 0; i < 16; ++i) O[s][d][i] *= al;
;             }
.LBB0_158:
	s_mov_b32 s8, 0
	v_readfirstlane_b32 s9, v163
	s_bitcmp1_b32 s9, 8
	s_cbranch_scc0 .Lprio_a32
	s_setprio 1
.Lprio_a32:
	ds_read_b128 v[222:225], v171 offset:35840
	ds_read_b128 v[240:243], v171 offset:36864
	ds_read_b128 v[244:247], v171 offset:37888
	ds_read_b128 v[248:251], v171 offset:38912
	ds_read_b128 v[128:131], v149
	ds_read_b128 v[132:135], v149 offset:4608
	ds_read_b128 v[136:139], v149 offset:32
	ds_read_b128 v[140:143], v149 offset:4640
	v_lshl_add_u64 v[226:227], v[154:155], 0, v[160:161]
	s_mov_b64 s[10:11], 0x84000
	v_lshl_add_u64 v[236:237], v[226:227], 0, s[10:11]
	v_lshl_add_u64 v[230:231], v[156:157], 0, v[160:161]
	s_mov_b64 s[10:11], 0x3000
	v_lshl_add_u64 v[230:231], v[230:231], 0, s[10:11]
	global_load_dwordx4 v[206:209], v[230:231], off offset:-4096
	global_load_dwordx4 v[210:213], v[230:231], off
	global_load_dwordx4 v[214:217], v[226:227], off offset:128
	global_load_dwordx4 v[218:221], v[236:237], off offset:128
	v_mov_b32_e32 v153, v152
	v_mov_b32_e32 v147, v146
	s_and_b32 s9, s8, 1
	s_mul_i32 s10, s9, 0x2400
	s_mul_i32 s11, s9, 0x2200
	v_add_u32_e32 v173, s10, v149
	v_add_u32_e32 v236, s11, v172
	v_add_u32_e32 v237, 0x5800, v236
	v_add_u32_e32 v236, 0x4800, v236
	s_waitcnt lgkmcnt(0)
	v_mfma_f32_32x32x16_bf16 v[80:95], v[128:131], v[222:225], 0
	v_mfma_f32_32x32x16_bf16 v[80:95], v[136:139], v[240:243], v[80:95]
	v_mfma_f32_32x32x16_bf16 v[64:79], v[132:135], v[222:225], 0
	v_mfma_f32_32x32x16_bf16 v[64:79], v[140:143], v[240:243], v[64:79]
	ds_read2_b64 v[96:99], v236 offset0:0 offset1:2
	ds_read2_b64 v[112:115], v237 offset0:32 offset1:34
	ds_read2_b64 v[100:103], v236 offset0:4 offset1:6
	ds_read2_b64 v[116:119], v237 offset0:36 offset1:38
	ds_read2_b64 v[104:107], v236 offset0:8 offset1:10
	ds_read2_b64 v[120:123], v237 offset0:40 offset1:42
	ds_read2_b64 v[108:111], v236 offset0:12 offset1:14
	ds_read2_b64 v[124:127], v237 offset0:44 offset1:46
	ds_read_b128 v[128:131], v173 offset:64
	ds_read_b128 v[132:135], v173 offset:4672
	ds_read_b128 v[136:139], v173 offset:96
	ds_read_b128 v[140:143], v173 offset:4704
	v_max3_f32 v233, v80, v81, v82
	v_max3_f32 v233, v233, v83, v84
	v_max3_f32 v233, v233, v85, v86
	v_max3_f32 v233, v233, v87, v88
	v_max3_f32 v233, v233, v89, v90
	v_max3_f32 v233, v233, v91, v92
	v_max3_f32 v233, v233, v93, v94
	v_max3_f32 v233, v233, v95, v64
	v_max3_f32 v233, v233, v65, v66
	v_max3_f32 v233, v233, v67, v68
	v_max3_f32 v233, v233, v69, v70
	v_max3_f32 v233, v233, v71, v72
	v_max3_f32 v233, v233, v73, v74
	v_max3_f32 v233, v233, v75, v76
	v_max3_f32 v233, v233, v77, v78
	v_max_f32_e32 v233, v233, v79
	v_mov_b32_e32 v234, v233
	s_nop 1
	v_permlane32_swap_b32_e32 v234, v233
	s_nop 0
	v_max_f32_e32 v233, v233, v234
	v_add_f32_e32 v234, 0x41000000, v152
	v_cmp_gt_f32_e32 vcc, v233, v234
	s_cbranch_vccz .Lat32_nors0f
	v_max_f32_e32 v239, v152, v233
	v_sub_f32_e32 v234, v152, v239
	v_exp_f32_e32 v234, v234
	v_mov_b32_e32 v152, v239
	v_mov_b32_e32 v153, v239
	v_mul_f32_e32 v151, v151, v234
	v_mul_f32_e32 v32, v32, v234
	v_mul_f32_e32 v33, v33, v234
	v_mul_f32_e32 v34, v34, v234
	v_mul_f32_e32 v35, v35, v234
	v_mul_f32_e32 v36, v36, v234
	v_mul_f32_e32 v37, v37, v234
	v_mul_f32_e32 v38, v38, v234
	v_mul_f32_e32 v39, v39, v234
	v_mul_f32_e32 v40, v40, v234
	v_mul_f32_e32 v41, v41, v234
	v_mul_f32_e32 v42, v42, v234
	v_mul_f32_e32 v43, v43, v234
	v_mul_f32_e32 v44, v44, v234
	v_mul_f32_e32 v45, v45, v234
	v_mul_f32_e32 v46, v46, v234
	v_mul_f32_e32 v47, v47, v234
	v_mul_f32_e32 v0, v0, v234
	v_mul_f32_e32 v1, v1, v234
	v_mul_f32_e32 v2, v2, v234
	v_mul_f32_e32 v3, v3, v234
	v_mul_f32_e32 v4, v4, v234
	v_mul_f32_e32 v5, v5, v234
	v_mul_f32_e32 v6, v6, v234
	v_mul_f32_e32 v7, v7, v234
	v_mul_f32_e32 v8, v8, v234
	v_mul_f32_e32 v9, v9, v234
	v_mul_f32_e32 v10, v10, v234
	v_mul_f32_e32 v11, v11, v234
	v_mul_f32_e32 v12, v12, v234
	v_mul_f32_e32 v13, v13, v234
	v_mul_f32_e32 v14, v14, v234
	v_mul_f32_e32 v15, v15, v234

; #define MFMA32(a, b, c) __builtin_amdgcn_mfma_f32_32x32x16_bf16((a), (b), (c), 0, 0, 0)
; template <int DK>
; DI void attn_item(const Params& p, int layer, int b, int hd, int qt, int ctxq, char* smem) {
;     ...
;             const f32x2 mref = {m_[s], m_[s]};
;             float ps = 0.f;
; #pragma unroll
;             for (int kb = 0; kb < 2; ++kb)
; #pragma unroll
;                 for (int i2 = 0; i2 < 8; ++i2) {
;                     f32x2 t = {x[kb][2 * i2], x[kb][2 * i2 + 1]};
;                     asm("v_pk_add_f32 %0, %1, %2 neg_lo:[0,1] neg_hi:[0,1]" : "=v"(t) : "v"(t), "v"(mref));
;                     const float e0 = __builtin_amdgcn_exp2f(t.x), e1 = __builtin_amdgcn_exp2f(t.y);
;                     x[kb][2 * i2] = e0; x[kb][2 * i2 + 1] = e1; ps += e0 + e1;
;                 }
;             l_[s] += ps;
; #pragma unroll
;             for (int kb = 0; kb < 2; ++kb)
; #pragma unroll
;                 for (int st = 0; st < 2; ++st) {
;                     u32x4 w;
;                     w.x = pk_bf16(x[kb][8 * st], x[kb][8 * st + 1]); w.y = pk_bf16(x[kb][8 * st + 2], x[kb][8 * st + 3]);
;                     w.z = pk_bf16(x[kb][8 * st + 4], x[kb][8 * st + 5]); w.w = pk_bf16(x[kb][8 * st + 6], x[kb][8 * st + 7]);
;                     const bf16x8 pfr = __builtin_bit_cast(bf16x8, w);
; #pragma unroll
;                     for (int d = 0; d < 2; ++d) {
;                         const bf16_t* vp = vb_ + (32 * d + r) * 68 + 32 * kb + 16 * st + 4 * h;
;                         const s16x4 lo = *(const s16x4*)vp, hi = *(const s16x4*)(vp + 8);
;                         const bf16x8 vf = __builtin_shufflevector(lo, hi, 0, 1, 2, 3, 4, 5, 6, 7);
;                         O[s][d] = MFMA32(vf, pfr, O[s][d]);
;                     }
;                 }
;         }
;         if (kt + 1 < nkt) {
;             bf16_t* wk = sK + (cur ^ 1) * 64 * 72; bf16_t* wv = sV + (cur ^ 1) * 64 * 68;
; #pragma unroll
;             for (int i = 0; i < 2; ++i) {
;                 *(u32x4*)(wk + (srow + 32 * i) * 72 + sc8) = rk[i];
;                 *(u32x2*)(wv + (srow + 32 * i) * 68 + sc8) = (u32x2){rv[i].x, rv[i].y}; *(u32x2*)(wv + (srow + 32 * i) * 68 + sc8 + 4) = (u32x2){rv[i].z, rv[i].w};
;             }
;         }
;         __syncthreads();
.Lat32_nors1:
	v_exp_f32_e32 v80, v80
	v_exp_f32_e32 v81, v81
	v_exp_f32_e32 v82, v82
	v_exp_f32_e32 v83, v83
	v_exp_f32_e32 v84, v84
	v_exp_f32_e32 v85, v85
	v_exp_f32_e32 v86, v86
	v_exp_f32_e32 v87, v87
	v_add_f32_e32 v236, v80, v82
	v_add_f32_e32 v237, v81, v83
	v_add_f32_e32 v236, v236, v84
	v_add_f32_e32 v237, v237, v85
	v_add_f32_e32 v236, v236, v86
	v_add_f32_e32 v237, v237, v87
	v_cvt_pk_bf16_f32 v80, v80, v81
	v_cvt_pk_bf16_f32 v81, v82, v83
	v_cvt_pk_bf16_f32 v82, v84, v85
	v_cvt_pk_bf16_f32 v83, v86, v87
	s_nop 1
	v_mfma_f32_32x32x16_bf16 v[48:63], v[96:99], v[80:83], v[48:63]
	v_mfma_f32_32x32x16_bf16 v[16:31], v[112:115], v[80:83], v[16:31]
	v_exp_f32_e32 v88, v88
	v_exp_f32_e32 v89, v89
	v_exp_f32_e32 v90, v90
	v_exp_f32_e32 v91, v91
	v_exp_f32_e32 v92, v92
	v_exp_f32_e32 v93, v93
	v_exp_f32_e32 v94, v94
	v_exp_f32_e32 v95, v95
	v_add_f32_e32 v236, v236, v88
	v_add_f32_e32 v237, v237, v89
	v_add_f32_e32 v236, v236, v90
	v_add_f32_e32 v237, v237, v91
	v_add_f32_e32 v236, v236, v92
	v_add_f32_e32 v237, v237, v93
	v_add_f32_e32 v236, v236, v94
	v_add_f32_e32 v237, v237, v95
	v_cvt_pk_bf16_f32 v88, v88, v89
	v_cvt_pk_bf16_f32 v89, v90, v91
	v_cvt_pk_bf16_f32 v90, v92, v93
	v_cvt_pk_bf16_f32 v91, v94, v95
	s_nop 1
	v_mfma_f32_32x32x16_bf16 v[48:63], v[100:103], v[88:91], v[48:63]
	v_mfma_f32_32x32x16_bf16 v[16:31], v[116:119], v[88:91], v[16:31]
	s_waitcnt lgkmcnt(0)
	s_barrier
	ds_read_b128 v[128:131], v173
	ds_read_b128 v[132:135], v173 offset:4608
	ds_read_b128 v[136:139], v173 offset:32
	ds_read_b128 v[140:143], v173 offset:4640
	v_exp_f32_e32 v64, v64
	v_exp_f32_e32 v65, v65
	v_exp_f32_e32 v66, v66
	v_exp_f32_e32 v67, v67
	v_exp_f32_e32 v68, v68
	v_exp_f32_e32 v69, v69
	v_exp_f32_e32 v70, v70
	v_exp_f32_e32 v71, v71
	v_add_f32_e32 v236, v236, v64
	v_add_f32_e32 v237, v237, v65
	v_add_f32_e32 v236, v236, v66
	v_add_f32_e32 v237, v237, v67
	v_add_f32_e32 v236, v236, v68
	v_add_f32_e32 v237, v237, v69
	v_add_f32_e32 v236, v236, v70
	v_add_f32_e32 v237, v237, v71
	v_cvt_pk_bf16_f32 v64, v64, v65
	v_cvt_pk_bf16_f32 v65, v66, v67
	v_cvt_pk_bf16_f32 v66, v68, v69
	v_cvt_pk_bf16_f32 v67, v70, v71
	s_nop 1
	v_mfma_f32_32x32x16_bf16 v[48:63], v[104:107], v[64:67], v[48:63]
	v_mfma_f32_32x32x16_bf16 v[16:31], v[120:123], v[64:67], v[16:31]
	v_exp_f32_e32 v72, v72
	v_exp_f32_e32 v73, v73
	v_exp_f32_e32 v74, v74
	v_exp_f32_e32 v75, v75
	v_exp_f32_e32 v76, v76
	v_exp_f32_e32 v77, v77
	v_exp_f32_e32 v78, v78
	v_exp_f32_e32 v79, v79
	v_add_f32_e32 v236, v236, v72
	v_add_f32_e32 v237, v237, v73
	v_add_f32_e32 v236, v236, v74
	v_add_f32_e32 v237, v237, v75
	v_add_f32_e32 v236, v236, v76
	v_add_f32_e32 v237, v237, v77
	v_add_f32_e32 v236, v236, v78
	v_add_f32_e32 v237, v237, v79
	v_cvt_pk_bf16_f32 v72, v72, v73
	v_cvt_pk_bf16_f32 v73, v74, v75
	v_cvt_pk_bf16_f32 v74, v76, v77
	v_cvt_pk_bf16_f32 v75, v78, v79
	v_add_f32_e32 v236, v236, v237
	v_add_f32_e32 v170, v170, v236
	v_mfma_f32_32x32x16_bf16 v[48:63], v[108:111], v[72:75], v[48:63]
	v_mfma_f32_32x32x16_bf16 v[16:31], v[124:127], v[72:75], v[16:31]
	s_add_i32 s8, s8, 1
	s_cmpk_eq_i32 s8, 0x83
	s_cbranch_scc0 .Lat32_loop
	s_waitcnt lgkmcnt(0)
	s_setprio 0

; DI int otid512() { int t = threadIdx.x; asm volatile("" : "+v"(t)); return t; }
; DI int rbid() { int t = blockIdx.x; asm volatile("" : "+s"(t)); return t; }
; DI int rgrid() { int t = gridDim.x; asm volatile("" : "+s"(t)); return t; }
; template <class Epi>
; DI void gemm_phase(const bf16_t* A, const bf16_t* Bt, int K, int mtiles, int ntiles, const Epi& epi, char* smem) {
;     bf16_t* sA = (bf16_t*)smem;
;     bf16_t* sB = sA + 2 * 256 * 72;
;     const int tid = otid512(), lane = tid & 63, wave = tid >> 6, wr = wave >> 2, wc = wave & 3, r = lane & 31, h = lane >> 5;
;     const int bid_ = rbid(), G_ = rgrid();
;     const int xcd = bid_ & 7, local = bid_ >> 3, nloc = G_ >> 3;
;     const int mper = mtiles >> 3, mrem = mtiles & 7;
;     const int mbeg = xcd * mper + (xcd < mrem ? xcd : mrem), mcnt = mper + (xcd < mrem ? 1 : 0);
;     const int total = mcnt * ntiles, pg = 4 * ntiles, nk = K >> 6;
;     const int srow = tid >> 3, skc = (tid & 7) * 8;
;     const int main_total = Epi::TAIL ? (total / nloc) * nloc : total;
;     int tcount = 0;
; DI void run_phase(int ph, char* smem) {
;     ...
;         EpiProj e{p.ACT, p.GATES, p.ml_gate_b + l * 16};
;         gemm_phase(p.H, wb + W_WIN, 1024, NT / 256, PWP / 256, e, smem);
.LBB0_312:
	s_and_b64 vcc, exec, s[0:1]
	s_cbranch_vccz .LBB0_332
	v_mov_b32_e32 v0, v163
	v_readlane_b32 s0, v252, 0
	s_ashr_i32 s8, s0, 3
	v_readlane_b32 s1, v253, 3
	s_cmpk_gt_i32 s8, 0x16a
	s_cbranch_scc1 .LBB0_332
	s_and_b32 s10, s0, 7
	s_ashr_i32 s9, s1, 3
	v_readlane_b32 s0, v254, 7
	v_readlane_b32 s44, v253, 22
	v_readlane_b32 s1, v254, 8
	s_lshl_b32 s0, s0, 4
	v_readlane_b32 s52, v253, 30
	v_readlane_b32 s53, v253, 31
	v_readlane_b32 s54, v253, 32
	v_readlane_b32 s55, v253, 33
	v_readlane_b32 s56, v253, 34
	v_readlane_b32 s57, v253, 35
	v_readlane_b32 s58, v253, 36
	v_readlane_b32 s59, v253, 37
	s_ashr_i32 s1, s0, 31
	v_readlane_b32 s48, v253, 26
	v_readlane_b32 s49, v253, 27
	v_readlane_b32 s52, v253, 49
	v_lshlrev_b32_e32 v1, 4, v0
	v_readlane_b32 s2, v254, 2
	s_lshl_b64 s[0:1], s[0:1], 2
	s_mov_b64 s[12:13], s[48:49]
	v_readlane_b32 s62, v253, 59
	v_readlane_b32 s63, v253, 60
	v_and_b32_e32 v2, 0x70, v1
	v_mov_b32_e32 v3, v161
	v_readlane_b32 s3, v254, 3
	v_ashrrev_i32_e32 v1, 1, v0
	v_and_b32_e32 v160, 31, v0
	v_ashrrev_i32_e32 v152, 3, v0
	s_add_u32 s0, s12, s0
	v_bfe_u32 v6, v0, 5, 1
	v_and_b32_e32 v153, 0xc0, v0
	v_lshl_add_u64 v[128:129], s[62:63], 0, v[2:3]
	v_lshl_add_u64 v[4:5], s[2:3], 0, v[2:3]
	s_mov_b64 s[4:5], 0x2100000
	v_and_b32_e32 v3, 0xffffff80, v1
	v_and_b32_e32 v0, 0xdf, v0
	s_addc_u32 s1, s13, s1
	s_add_i32 s6, 16, 0x12000
	v_lshl_add_u64 v[130:131], v[4:5], 0, s[4:5]
	v_or_b32_e32 v1, v3, v160
	s_movk_i32 s4, 0x90
	v_lshlrev_b32_e32 v4, 4, v6
	v_mul_u32_u24_e32 v0, 0x90, v0
	v_mul_lo_u32 v1, v1, s4
	v_add3_u32 v155, s6, v0, v4
	v_mul_lo_u32 v0, v152, s4
	v_readlane_b32 s66, v253, 63
	v_readlane_b32 s67, v254, 0
	v_add3_u32 v154, 16, v1, v4
	v_add3_u32 v156, 16, v2, v0
	v_add3_u32 v157, s6, v2, v0
	v_lshlrev_b32_e32 v0, 2, v160
	v_mov_b32_e32 v1, v161
	s_mul_i32 s10, s10, 33
	v_readlane_b32 s53, v253, 50
	v_readlane_b32 s54, v253, 51
	v_readlane_b32 s55, v253, 52
	v_readlane_b32 s56, v253, 53
	v_readlane_b32 s57, v253, 54
	v_readlane_b32 s58, v253, 55
	v_readlane_b32 s59, v253, 56
	v_readlane_b32 s60, v253, 57
	v_readlane_b32 s61, v253, 58
	v_readlane_b32 s64, v253, 61
	v_readlane_b32 s65, v253, 62
	v_cmp_gt_u32_e32 vcc, 16, v160
	v_lshl_add_u64 v[132:133], s[0:1], 0, v[0:1]
	v_lshl_add_u64 v[134:135], s[66:67], 0, v[0:1]
	v_lshl_or_b32 v158, v6, 2, v3
	v_readlane_b32 s45, v253, 23
	v_readlane_b32 s46, v253, 24
	v_readlane_b32 s47, v253, 25
	v_readlane_b32 s50, v253, 28
	v_readlane_b32 s51, v253, 29
	v_readfirstlane_b32 s98, v163
	s_bitcmp1_b32 s98, 8
	s_cbranch_scc0 .Lprio_pj
	s_setprio 1
.Lprio_pj:
	s_branch .LBB0_316
.LBB0_315:
	s_or_b64 exec, exec, s[0:1]
	s_add_i32 s8, s8, s9
	s_cmpk_gt_i32 s8, 0x16a
	s_cbranch_scc1 .LBB0_332

; template <class Epi>
; DI void gemm_phase(const bf16_t* A, const bf16_t* Bt, int K, int mtiles, int ntiles, const Epi& epi, char* smem) {
;     ...
;     }
;     if (Epi::TAIL) {
.LBB0_332:
	s_setprio 0
	s_mov_b64 s[0:1], 0

; template <class Epi>
; DI void gemm_phase(const bf16_t* A, const bf16_t* Bt, int K, int mtiles, int ntiles, const Epi& epi, char* smem) {
;     ...
;     for (int it = local; it < main_total; it += nloc) {
;         const int grp = it / pg, rem = it - grp * pg;
;         const int gl = mcnt - grp * 4, gsz = gl < 4 ? gl : 4;
;         const int mt = mbeg + grp * 4 + rem % gsz, nt = rem / gsz;
;         const bf16_t* Ag = A + (size_t)(mt * 256 + srow) * K + skc;
;         const bf16_t* Bg = Bt + (size_t)(nt * 256 + srow) * K + skc;
;         float* sst = (float*)(smem + 2 * HALF_LDS) + (tcount & 1) * 512; ++tcount;
;         epi.prefetch(mt * 256, tid, sst);
;         u32x4 ra[4], rb[4];
; #pragma unroll
;         for (int i = 0; i < 4; ++i) { ra[i] = *(const u32x4*)(Ag + (size_t)(64 * i) * K); rb[i] = *(const u32x4*)(Bg + (size_t)(64 * i) * K); }
; #pragma unroll
;         for (int i = 0; i < 4; ++i) { *(u32x4*)(sA + (srow + 64 * i) * 72 + skc) = ra[i]; *(u32x4*)(sB + (srow + 64 * i) * 72 + skc) = rb[i]; }
; #pragma unroll
;         for (int i = 0; i < 4; ++i) { ra[i] = *(const u32x4*)(Ag + (size_t)(64 * i) * K + 64); rb[i] = *(const u32x4*)(Bg + (size_t)(64 * i) * K + 64); }
;         __syncthreads();
;         f32x16 acc[4][2];
; #pragma unroll
;         for (int a = 0; a < 4; ++a)
; #pragma unroll
;             for (int b = 0; b < 2; ++b)
; #pragma unroll
;                 for (int i = 0; i < 16; ++i) acc[a][b][i] = 0.f;
;         for (int kt = 0; kt < nk; ++kt) {
.LBB0_603:
	v_readfirstlane_b32 s0, v163
	s_bitcmp1_b32 s0, 8
	s_cbranch_scc0 .Lprio_sw
	s_setprio 1

; template <class Epi>
; DI void gemm_phase(const bf16_t* A, const bf16_t* Bt, int K, int mtiles, int ntiles, const Epi& epi, char* smem) {
;     ...
;     }
;     if (Epi::TAIL) {
.LBB0_604:
	s_setprio 0
	s_mov_b64 s[4:5], 0
